# output rows stored non-temporal from the fused final epilogue
# baseline (speedup 1.0000x reference)
.Lfz_synced:
	s_mov_b64 exec, s[20:21]
	s_barrier
	v_mul_u32_u24_e32 v154, 0x4800, v129
	v_add_u32_e32 v154, v154, v152
	v_lshlrev_b32_e32 v154, 2, v154
	v_add_u32_e32 v155, 0x9000, v154
	global_load_dword v180, v154, s[100:101] offset:0 sc1
	global_load_dword v181, v155, s[100:101] offset:0 sc1
	global_load_dword v182, v154, s[100:101] offset:64 sc1
	global_load_dword v183, v155, s[100:101] offset:64 sc1
	global_load_dword v184, v154, s[100:101] offset:128 sc1
	global_load_dword v185, v155, s[100:101] offset:128 sc1
	global_load_dword v186, v154, s[100:101] offset:192 sc1
	global_load_dword v187, v155, s[100:101] offset:192 sc1
	global_load_dword v188, v154, s[100:101] offset:512 sc1
	global_load_dword v189, v155, s[100:101] offset:512 sc1
	global_load_dword v190, v154, s[100:101] offset:576 sc1
	global_load_dword v191, v155, s[100:101] offset:576 sc1
	global_load_dword v192, v154, s[100:101] offset:640 sc1
	global_load_dword v193, v155, s[100:101] offset:640 sc1
	global_load_dword v194, v154, s[100:101] offset:704 sc1
	global_load_dword v195, v155, s[100:101] offset:704 sc1
	s_waitcnt vmcnt(0)
	v_add_f32_e32 v160, v180, v181
	v_add_f32_e32 v161, v182, v183
	v_add_f32_e32 v162, v184, v185
	v_add_f32_e32 v163, v186, v187
	v_add_f32_e32 v164, v188, v189
	v_add_f32_e32 v165, v190, v191
	v_add_f32_e32 v166, v192, v193
	v_add_f32_e32 v167, v194, v195
	v_mov_b32_e32 v168, v160
	v_mov_b32_e32 v169, v161
	v_mov_b32_e32 v170, v162
	v_mov_b32_e32 v171, v163
	v_mov_b32_e32 v172, v164
	v_mov_b32_e32 v173, v165
	v_mov_b32_e32 v174, v166
	v_mov_b32_e32 v175, v167
	s_nop 1
	v_permlane32_swap_b32_e32 v160, v168
	v_permlane32_swap_b32_e32 v161, v169
	v_permlane32_swap_b32_e32 v162, v170
	v_permlane32_swap_b32_e32 v163, v171
	v_permlane32_swap_b32_e32 v164, v172
	v_permlane32_swap_b32_e32 v165, v173
	v_permlane32_swap_b32_e32 v166, v174
	v_permlane32_swap_b32_e32 v167, v175
	s_nop 1
	v_add_f32_e32 v160, v160, v168
	v_add_f32_e32 v161, v161, v169
	v_add_f32_e32 v162, v162, v170
	v_add_f32_e32 v163, v163, v171
	v_add_f32_e32 v164, v164, v172
	v_add_f32_e32 v165, v165, v173
	v_add_f32_e32 v166, v166, v174
	v_add_f32_e32 v167, v167, v175
	v_mov_b32_e32 v168, v160
	v_mov_b32_e32 v169, v161
	v_mov_b32_e32 v170, v162
	v_mov_b32_e32 v171, v163
	v_mov_b32_e32 v172, v164
	v_mov_b32_e32 v173, v165
	v_mov_b32_e32 v174, v166
	v_mov_b32_e32 v175, v167
	s_nop 1
	v_permlane16_swap_b32_e32 v160, v168
	v_permlane16_swap_b32_e32 v161, v169
	v_permlane16_swap_b32_e32 v162, v170
	v_permlane16_swap_b32_e32 v163, v171
	v_permlane16_swap_b32_e32 v164, v172
	v_permlane16_swap_b32_e32 v165, v173
	v_permlane16_swap_b32_e32 v166, v174
	v_permlane16_swap_b32_e32 v167, v175
	s_nop 1
	v_add_f32_e32 v160, v160, v168
	v_add_f32_e32 v161, v161, v169
	v_add_f32_e32 v162, v162, v170
	v_add_f32_e32 v163, v163, v171
	v_add_f32_e32 v164, v164, v172
	v_add_f32_e32 v165, v165, v173
	v_add_f32_e32 v166, v166, v174
	v_add_f32_e32 v167, v167, v175
	v_mov_b32_e32 v178, 0x358637bd
	v_mov_b32_e32 v179, 0x260
	v_fmamk_f32 v160, v160, 0x3a000000, v178
	v_mul_f32_e32 v169, 0x4f800000, v160
	v_cmp_gt_f32_e32 vcc, 0xf800000, v160
	s_nop 1
	v_cndmask_b32_e32 v168, v160, v169, vcc
	v_sqrt_f32_e32 v169, v168
	s_nop 0
	v_add_u32_e32 v170, -1, v169
	v_fma_f32 v171, -v170, v169, v168
	v_cmp_ge_f32_e64 s[18:19], 0, v171
	v_add_u32_e32 v171, 1, v169
	s_nop 0
	v_cndmask_b32_e64 v170, v169, v170, s[18:19]
	v_fma_f32 v169, -v171, v169, v168
	v_cmp_lt_f32_e64 s[18:19], 0, v169
	s_nop 1
	v_cndmask_b32_e64 v169, v170, v171, s[18:19]
	v_mul_f32_e32 v170, 0x37800000, v169
	v_cndmask_b32_e32 v169, v169, v170, vcc
	v_cmp_class_f32_e32 vcc, v168, v179
	s_nop 1
	v_cndmask_b32_e32 v168, v169, v168, vcc
	v_div_scale_f32 v169, s[18:19], v168, v168, 1.0
	v_rcp_f32_e32 v170, v169
	s_nop 1
	v_fma_f32 v171, -v169, v170, 1.0
	v_fmac_f32_e32 v170, v171, v170
	v_div_scale_f32 v171, vcc, 1.0, v168, 1.0
	v_mul_f32_e32 v172, v171, v170
	v_fma_f32 v173, -v169, v172, v171
	v_fmac_f32_e32 v172, v173, v170
	v_fma_f32 v169, -v169, v172, v171
	s_nop 0
	v_div_fmas_f32 v169, v169, v170, v172
	v_div_fixup_f32 v180, v169, v168, 1.0
	v_fmamk_f32 v161, v161, 0x3a000000, v178
	v_mul_f32_e32 v169, 0x4f800000, v161
	v_cmp_gt_f32_e32 vcc, 0xf800000, v161
	s_nop 1
	v_cndmask_b32_e32 v168, v161, v169, vcc
	v_sqrt_f32_e32 v169, v168
	s_nop 0
	v_add_u32_e32 v170, -1, v169
	v_fma_f32 v171, -v170, v169, v168
	v_cmp_ge_f32_e64 s[18:19], 0, v171
	v_add_u32_e32 v171, 1, v169
	s_nop 0
	v_cndmask_b32_e64 v170, v169, v170, s[18:19]
	v_fma_f32 v169, -v171, v169, v168
	v_cmp_lt_f32_e64 s[18:19], 0, v169
	s_nop 1
	v_cndmask_b32_e64 v169, v170, v171, s[18:19]
	v_mul_f32_e32 v170, 0x37800000, v169
	v_cndmask_b32_e32 v169, v169, v170, vcc
	v_cmp_class_f32_e32 vcc, v168, v179
	s_nop 1
	v_cndmask_b32_e32 v168, v169, v168, vcc
	v_div_scale_f32 v169, s[18:19], v168, v168, 1.0
	v_rcp_f32_e32 v170, v169
	s_nop 1
	v_fma_f32 v171, -v169, v170, 1.0
	v_fmac_f32_e32 v170, v171, v170
	v_div_scale_f32 v171, vcc, 1.0, v168, 1.0
	v_mul_f32_e32 v172, v171, v170
	v_fma_f32 v173, -v169, v172, v171
	v_fmac_f32_e32 v172, v173, v170
	v_fma_f32 v169, -v169, v172, v171
	s_nop 0
	v_div_fmas_f32 v169, v169, v170, v172
	v_div_fixup_f32 v182, v169, v168, 1.0
	v_fmamk_f32 v162, v162, 0x3a000000, v178
	v_mul_f32_e32 v169, 0x4f800000, v162
	v_cmp_gt_f32_e32 vcc, 0xf800000, v162
	s_nop 1
	v_cndmask_b32_e32 v168, v162, v169, vcc
	v_sqrt_f32_e32 v169, v168
	s_nop 0
	v_add_u32_e32 v170, -1, v169
	v_fma_f32 v171, -v170, v169, v168
	v_cmp_ge_f32_e64 s[18:19], 0, v171
	v_add_u32_e32 v171, 1, v169
	s_nop 0
	v_cndmask_b32_e64 v170, v169, v170, s[18:19]
	v_fma_f32 v169, -v171, v169, v168
	v_cmp_lt_f32_e64 s[18:19], 0, v169
	s_nop 1
	v_cndmask_b32_e64 v169, v170, v171, s[18:19]
	v_mul_f32_e32 v170, 0x37800000, v169
	v_cndmask_b32_e32 v169, v169, v170, vcc
	v_cmp_class_f32_e32 vcc, v168, v179
	s_nop 1
	v_cndmask_b32_e32 v168, v169, v168, vcc
	v_div_scale_f32 v169, s[18:19], v168, v168, 1.0
	v_rcp_f32_e32 v170, v169
	s_nop 1
	v_fma_f32 v171, -v169, v170, 1.0
	v_fmac_f32_e32 v170, v171, v170
	v_div_scale_f32 v171, vcc, 1.0, v168, 1.0
	v_mul_f32_e32 v172, v171, v170
	v_fma_f32 v173, -v169, v172, v171
	v_fmac_f32_e32 v172, v173, v170
	v_fma_f32 v169, -v169, v172, v171
	s_nop 0
	v_div_fmas_f32 v169, v169, v170, v172
	v_div_fixup_f32 v184, v169, v168, 1.0
	v_fmamk_f32 v163, v163, 0x3a000000, v178
	v_mul_f32_e32 v169, 0x4f800000, v163
	v_cmp_gt_f32_e32 vcc, 0xf800000, v163
	s_nop 1
	v_cndmask_b32_e32 v168, v163, v169, vcc
	v_sqrt_f32_e32 v169, v168
	s_nop 0
	v_add_u32_e32 v170, -1, v169
	v_fma_f32 v171, -v170, v169, v168
	v_cmp_ge_f32_e64 s[18:19], 0, v171
	v_add_u32_e32 v171, 1, v169
	s_nop 0
	v_cndmask_b32_e64 v170, v169, v170, s[18:19]
	v_fma_f32 v169, -v171, v169, v168
	v_cmp_lt_f32_e64 s[18:19], 0, v169
	s_nop 1
	v_cndmask_b32_e64 v169, v170, v171, s[18:19]
	v_mul_f32_e32 v170, 0x37800000, v169
	v_cndmask_b32_e32 v169, v169, v170, vcc
	v_cmp_class_f32_e32 vcc, v168, v179
	s_nop 1
	v_cndmask_b32_e32 v168, v169, v168, vcc
	v_div_scale_f32 v169, s[18:19], v168, v168, 1.0
	v_rcp_f32_e32 v170, v169
	s_nop 1
	v_fma_f32 v171, -v169, v170, 1.0
	v_fmac_f32_e32 v170, v171, v170
	v_div_scale_f32 v171, vcc, 1.0, v168, 1.0
	v_mul_f32_e32 v172, v171, v170
	v_fma_f32 v173, -v169, v172, v171
	v_fmac_f32_e32 v172, v173, v170
	v_fma_f32 v169, -v169, v172, v171
	s_nop 0
	v_div_fmas_f32 v169, v169, v170, v172
	v_div_fixup_f32 v186, v169, v168, 1.0
	v_fmamk_f32 v164, v164, 0x3a000000, v178
	v_mul_f32_e32 v169, 0x4f800000, v164
	v_cmp_gt_f32_e32 vcc, 0xf800000, v164
	s_nop 1
	v_cndmask_b32_e32 v168, v164, v169, vcc
	v_sqrt_f32_e32 v169, v168
	s_nop 0
	v_add_u32_e32 v170, -1, v169
	v_fma_f32 v171, -v170, v169, v168
	v_cmp_ge_f32_e64 s[18:19], 0, v171
	v_add_u32_e32 v171, 1, v169
	s_nop 0
	v_cndmask_b32_e64 v170, v169, v170, s[18:19]
	v_fma_f32 v169, -v171, v169, v168
	v_cmp_lt_f32_e64 s[18:19], 0, v169
	s_nop 1
	v_cndmask_b32_e64 v169, v170, v171, s[18:19]
	v_mul_f32_e32 v170, 0x37800000, v169
	v_cndmask_b32_e32 v169, v169, v170, vcc
	v_cmp_class_f32_e32 vcc, v168, v179
	s_nop 1
	v_cndmask_b32_e32 v168, v169, v168, vcc
	v_div_scale_f32 v169, s[18:19], v168, v168, 1.0
	v_rcp_f32_e32 v170, v169
	s_nop 1
	v_fma_f32 v171, -v169, v170, 1.0
	v_fmac_f32_e32 v170, v171, v170
	v_div_scale_f32 v171, vcc, 1.0, v168, 1.0
	v_mul_f32_e32 v172, v171, v170
	v_fma_f32 v173, -v169, v172, v171
	v_fmac_f32_e32 v172, v173, v170
	v_fma_f32 v169, -v169, v172, v171
	s_nop 0
	v_div_fmas_f32 v169, v169, v170, v172
	v_div_fixup_f32 v188, v169, v168, 1.0
	v_fmamk_f32 v165, v165, 0x3a000000, v178
	v_mul_f32_e32 v169, 0x4f800000, v165
	v_cmp_gt_f32_e32 vcc, 0xf800000, v165
	s_nop 1
	v_cndmask_b32_e32 v168, v165, v169, vcc
	v_sqrt_f32_e32 v169, v168
	s_nop 0
	v_add_u32_e32 v170, -1, v169
	v_fma_f32 v171, -v170, v169, v168
	v_cmp_ge_f32_e64 s[18:19], 0, v171
	v_add_u32_e32 v171, 1, v169
	s_nop 0
	v_cndmask_b32_e64 v170, v169, v170, s[18:19]
	v_fma_f32 v169, -v171, v169, v168
	v_cmp_lt_f32_e64 s[18:19], 0, v169
	s_nop 1
	v_cndmask_b32_e64 v169, v170, v171, s[18:19]
	v_mul_f32_e32 v170, 0x37800000, v169
	v_cndmask_b32_e32 v169, v169, v170, vcc
	v_cmp_class_f32_e32 vcc, v168, v179
	s_nop 1
	v_cndmask_b32_e32 v168, v169, v168, vcc
	v_div_scale_f32 v169, s[18:19], v168, v168, 1.0
	v_rcp_f32_e32 v170, v169
	s_nop 1
	v_fma_f32 v171, -v169, v170, 1.0
	v_fmac_f32_e32 v170, v171, v170
	v_div_scale_f32 v171, vcc, 1.0, v168, 1.0
	v_mul_f32_e32 v172, v171, v170
	v_fma_f32 v173, -v169, v172, v171
	v_fmac_f32_e32 v172, v173, v170
	v_fma_f32 v169, -v169, v172, v171
	s_nop 0
	v_div_fmas_f32 v169, v169, v170, v172
	v_div_fixup_f32 v190, v169, v168, 1.0
	v_fmamk_f32 v166, v166, 0x3a000000, v178
	v_mul_f32_e32 v169, 0x4f800000, v166
	v_cmp_gt_f32_e32 vcc, 0xf800000, v166
	s_nop 1
	v_cndmask_b32_e32 v168, v166, v169, vcc
	v_sqrt_f32_e32 v169, v168
	s_nop 0
	v_add_u32_e32 v170, -1, v169
	v_fma_f32 v171, -v170, v169, v168
	v_cmp_ge_f32_e64 s[18:19], 0, v171
	v_add_u32_e32 v171, 1, v169
	s_nop 0
	v_cndmask_b32_e64 v170, v169, v170, s[18:19]
	v_fma_f32 v169, -v171, v169, v168
	v_cmp_lt_f32_e64 s[18:19], 0, v169
	s_nop 1
	v_cndmask_b32_e64 v169, v170, v171, s[18:19]
	v_mul_f32_e32 v170, 0x37800000, v169
	v_cndmask_b32_e32 v169, v169, v170, vcc
	v_cmp_class_f32_e32 vcc, v168, v179
	s_nop 1
	v_cndmask_b32_e32 v168, v169, v168, vcc
	v_div_scale_f32 v169, s[18:19], v168, v168, 1.0
	v_rcp_f32_e32 v170, v169
	s_nop 1
	v_fma_f32 v171, -v169, v170, 1.0
	v_fmac_f32_e32 v170, v171, v170
	v_div_scale_f32 v171, vcc, 1.0, v168, 1.0
	v_mul_f32_e32 v172, v171, v170
	v_fma_f32 v173, -v169, v172, v171
	v_fmac_f32_e32 v172, v173, v170
	v_fma_f32 v169, -v169, v172, v171
	s_nop 0
	v_div_fmas_f32 v169, v169, v170, v172
	v_div_fixup_f32 v192, v169, v168, 1.0
	v_fmamk_f32 v167, v167, 0x3a000000, v178
	v_mul_f32_e32 v169, 0x4f800000, v167
	v_cmp_gt_f32_e32 vcc, 0xf800000, v167
	s_nop 1
	v_cndmask_b32_e32 v168, v167, v169, vcc
	v_sqrt_f32_e32 v169, v168
	s_nop 0
	v_add_u32_e32 v170, -1, v169
	v_fma_f32 v171, -v170, v169, v168
	v_cmp_ge_f32_e64 s[18:19], 0, v171
	v_add_u32_e32 v171, 1, v169
	s_nop 0
	v_cndmask_b32_e64 v170, v169, v170, s[18:19]
	v_fma_f32 v169, -v171, v169, v168
	v_cmp_lt_f32_e64 s[18:19], 0, v169
	s_nop 1
	v_cndmask_b32_e64 v169, v170, v171, s[18:19]
	v_mul_f32_e32 v170, 0x37800000, v169
	v_cndmask_b32_e32 v169, v169, v170, vcc
	v_cmp_class_f32_e32 vcc, v168, v179
	s_nop 1
	v_cndmask_b32_e32 v168, v169, v168, vcc
	v_div_scale_f32 v169, s[18:19], v168, v168, 1.0
	v_rcp_f32_e32 v170, v169
	s_nop 1
	v_fma_f32 v171, -v169, v170, 1.0
	v_fmac_f32_e32 v170, v171, v170
	v_div_scale_f32 v171, vcc, 1.0, v168, 1.0
	v_mul_f32_e32 v172, v171, v170
	v_fma_f32 v173, -v169, v172, v171
	v_fmac_f32_e32 v172, v173, v170
	v_fma_f32 v169, -v169, v172, v171
	s_nop 0
	v_div_fmas_f32 v169, v169, v170, v172
	v_div_fixup_f32 v194, v169, v168, 1.0
	v_readlane_b32 s100, v253, 3
	v_readlane_b32 s101, v253, 4
	s_add_u32 s100, s100, 0
	s_addc_u32 s101, s101, 0
	s_mul_hi_i32 s18, s95, 0x38e38e39
	s_lshr_b32 s19, s18, 31
	s_ashr_i32 s18, s18, 1
	s_add_i32 s18, s18, s19
	s_add_i32 s18, s18, 1
	s_lshl_b32 s18, s18, 8
	v_subrev_u32_e32 v152, s18, v152
	s_waitcnt vmcnt(0)
	v_add_u32_e32 v154, 0, v152
	v_lshl_add_u32 v154, v154, 13, v153
	v_pk_mul_f32 v[124:125], v[124:125], v[180:181] op_sel_hi:[1,0]
	v_pk_mul_f32 v[126:127], v[126:127], v[180:181] op_sel_hi:[1,0]
	v_pk_mul_f32 v[124:125], v[124:125], v[132:133]
	v_pk_mul_f32 v[126:127], v[126:127], v[134:135]
	v_pk_mul_f32 v[120:121], v[120:121], v[180:181] op_sel_hi:[1,0]
	v_pk_mul_f32 v[122:123], v[122:123], v[180:181] op_sel_hi:[1,0]
	v_pk_mul_f32 v[120:121], v[120:121], v[136:137]
	v_pk_mul_f32 v[122:123], v[122:123], v[138:139]
	v_pk_mul_f32 v[104:105], v[104:105], v[180:181] op_sel_hi:[1,0]
	v_pk_mul_f32 v[106:107], v[106:107], v[180:181] op_sel_hi:[1,0]
	v_pk_mul_f32 v[104:105], v[104:105], v[140:141]
	v_pk_mul_f32 v[106:107], v[106:107], v[142:143]
	v_pk_mul_f32 v[96:97], v[96:97], v[180:181] op_sel_hi:[1,0]
	v_pk_mul_f32 v[98:99], v[98:99], v[180:181] op_sel_hi:[1,0]
	v_pk_mul_f32 v[96:97], v[96:97], v[244:245]
	v_pk_mul_f32 v[98:99], v[98:99], v[246:247]
	global_store_dwordx4 v154, v[124:127], s[100:101] offset:0 nt
	global_store_dwordx4 v154, v[120:123], s[100:101] offset:64 nt
	global_store_dwordx4 v154, v[104:107], s[100:101] offset:512 nt
	global_store_dwordx4 v154, v[96:99], s[100:101] offset:576 nt
	v_add_u32_e32 v154, 16, v152
	v_lshl_add_u32 v154, v154, 13, v153
	v_pk_mul_f32 v[116:117], v[116:117], v[182:183] op_sel_hi:[1,0]
	v_pk_mul_f32 v[118:119], v[118:119], v[182:183] op_sel_hi:[1,0]
	v_pk_mul_f32 v[116:117], v[116:117], v[132:133]
	v_pk_mul_f32 v[118:119], v[118:119], v[134:135]
	v_pk_mul_f32 v[112:113], v[112:113], v[182:183] op_sel_hi:[1,0]
	v_pk_mul_f32 v[114:115], v[114:115], v[182:183] op_sel_hi:[1,0]
	v_pk_mul_f32 v[112:113], v[112:113], v[136:137]
	v_pk_mul_f32 v[114:115], v[114:115], v[138:139]
	v_pk_mul_f32 v[88:89], v[88:89], v[182:183] op_sel_hi:[1,0]
	v_pk_mul_f32 v[90:91], v[90:91], v[182:183] op_sel_hi:[1,0]
	v_pk_mul_f32 v[88:89], v[88:89], v[140:141]
	v_pk_mul_f32 v[90:91], v[90:91], v[142:143]
	v_pk_mul_f32 v[84:85], v[84:85], v[182:183] op_sel_hi:[1,0]
	v_pk_mul_f32 v[86:87], v[86:87], v[182:183] op_sel_hi:[1,0]
	v_pk_mul_f32 v[84:85], v[84:85], v[244:245]
	v_pk_mul_f32 v[86:87], v[86:87], v[246:247]
	global_store_dwordx4 v154, v[116:119], s[100:101] offset:0 nt
	global_store_dwordx4 v154, v[112:115], s[100:101] offset:64 nt
	global_store_dwordx4 v154, v[88:91], s[100:101] offset:512 nt
	global_store_dwordx4 v154, v[84:87], s[100:101] offset:576 nt
	v_add_u32_e32 v154, 32, v152
	v_lshl_add_u32 v154, v154, 13, v153
	v_pk_mul_f32 v[108:109], v[108:109], v[184:185] op_sel_hi:[1,0]
	v_pk_mul_f32 v[110:111], v[110:111], v[184:185] op_sel_hi:[1,0]
	v_pk_mul_f32 v[108:109], v[108:109], v[132:133]
	v_pk_mul_f32 v[110:111], v[110:111], v[134:135]
	v_pk_mul_f32 v[100:101], v[100:101], v[184:185] op_sel_hi:[1,0]
	v_pk_mul_f32 v[102:103], v[102:103], v[184:185] op_sel_hi:[1,0]
	v_pk_mul_f32 v[100:101], v[100:101], v[136:137]
	v_pk_mul_f32 v[102:103], v[102:103], v[138:139]
	v_pk_mul_f32 v[80:81], v[80:81], v[184:185] op_sel_hi:[1,0]
	v_pk_mul_f32 v[82:83], v[82:83], v[184:185] op_sel_hi:[1,0]
	v_pk_mul_f32 v[80:81], v[80:81], v[140:141]
	v_pk_mul_f32 v[82:83], v[82:83], v[142:143]
	v_pk_mul_f32 v[76:77], v[76:77], v[184:185] op_sel_hi:[1,0]
	v_pk_mul_f32 v[78:79], v[78:79], v[184:185] op_sel_hi:[1,0]
	v_pk_mul_f32 v[76:77], v[76:77], v[244:245]
	v_pk_mul_f32 v[78:79], v[78:79], v[246:247]
	global_store_dwordx4 v154, v[108:111], s[100:101] offset:0 nt
	global_store_dwordx4 v154, v[100:103], s[100:101] offset:64 nt
	global_store_dwordx4 v154, v[80:83], s[100:101] offset:512 nt
	global_store_dwordx4 v154, v[76:79], s[100:101] offset:576 nt
	v_add_u32_e32 v154, 48, v152
	v_lshl_add_u32 v154, v154, 13, v153
	v_pk_mul_f32 v[92:93], v[92:93], v[186:187] op_sel_hi:[1,0]
	v_pk_mul_f32 v[94:95], v[94:95], v[186:187] op_sel_hi:[1,0]
	v_pk_mul_f32 v[92:93], v[92:93], v[132:133]
	v_pk_mul_f32 v[94:95], v[94:95], v[134:135]
	v_pk_mul_f32 v[72:73], v[72:73], v[186:187] op_sel_hi:[1,0]
	v_pk_mul_f32 v[74:75], v[74:75], v[186:187] op_sel_hi:[1,0]
	v_pk_mul_f32 v[72:73], v[72:73], v[136:137]
	v_pk_mul_f32 v[74:75], v[74:75], v[138:139]
	v_pk_mul_f32 v[68:69], v[68:69], v[186:187] op_sel_hi:[1,0]
	v_pk_mul_f32 v[70:71], v[70:71], v[186:187] op_sel_hi:[1,0]
	v_pk_mul_f32 v[68:69], v[68:69], v[140:141]
	v_pk_mul_f32 v[70:71], v[70:71], v[142:143]
	v_pk_mul_f32 v[64:65], v[64:65], v[186:187] op_sel_hi:[1,0]
	v_pk_mul_f32 v[66:67], v[66:67], v[186:187] op_sel_hi:[1,0]
	v_pk_mul_f32 v[64:65], v[64:65], v[244:245]
	v_pk_mul_f32 v[66:67], v[66:67], v[246:247]
	global_store_dwordx4 v154, v[92:95], s[100:101] offset:0 nt
	global_store_dwordx4 v154, v[72:75], s[100:101] offset:64 nt
	global_store_dwordx4 v154, v[68:71], s[100:101] offset:512 nt
	global_store_dwordx4 v154, v[64:67], s[100:101] offset:576 nt
	v_add_u32_e32 v154, 128, v152
	v_lshl_add_u32 v154, v154, 13, v153
	v_pk_mul_f32 v[60:61], v[60:61], v[188:189] op_sel_hi:[1,0]
	v_pk_mul_f32 v[62:63], v[62:63], v[188:189] op_sel_hi:[1,0]
	v_pk_mul_f32 v[60:61], v[60:61], v[132:133]
	v_pk_mul_f32 v[62:63], v[62:63], v[134:135]
	v_pk_mul_f32 v[56:57], v[56:57], v[188:189] op_sel_hi:[1,0]
	v_pk_mul_f32 v[58:59], v[58:59], v[188:189] op_sel_hi:[1,0]
	v_pk_mul_f32 v[56:57], v[56:57], v[136:137]
	v_pk_mul_f32 v[58:59], v[58:59], v[138:139]
	v_pk_mul_f32 v[40:41], v[40:41], v[188:189] op_sel_hi:[1,0]
	v_pk_mul_f32 v[42:43], v[42:43], v[188:189] op_sel_hi:[1,0]
	v_pk_mul_f32 v[40:41], v[40:41], v[140:141]
	v_pk_mul_f32 v[42:43], v[42:43], v[142:143]
	v_pk_mul_f32 v[36:37], v[36:37], v[188:189] op_sel_hi:[1,0]
	v_pk_mul_f32 v[38:39], v[38:39], v[188:189] op_sel_hi:[1,0]
	v_pk_mul_f32 v[36:37], v[36:37], v[244:245]
	v_pk_mul_f32 v[38:39], v[38:39], v[246:247]
	global_store_dwordx4 v154, v[60:63], s[100:101] offset:0 nt
	global_store_dwordx4 v154, v[56:59], s[100:101] offset:64 nt
	global_store_dwordx4 v154, v[40:43], s[100:101] offset:512 nt
	global_store_dwordx4 v154, v[36:39], s[100:101] offset:576 nt
	v_add_u32_e32 v154, 144, v152
	v_lshl_add_u32 v154, v154, 13, v153
	v_pk_mul_f32 v[52:53], v[52:53], v[190:191] op_sel_hi:[1,0]
	v_pk_mul_f32 v[54:55], v[54:55], v[190:191] op_sel_hi:[1,0]
	v_pk_mul_f32 v[52:53], v[52:53], v[132:133]
	v_pk_mul_f32 v[54:55], v[54:55], v[134:135]
	v_pk_mul_f32 v[48:49], v[48:49], v[190:191] op_sel_hi:[1,0]
	v_pk_mul_f32 v[50:51], v[50:51], v[190:191] op_sel_hi:[1,0]
	v_pk_mul_f32 v[48:49], v[48:49], v[136:137]
	v_pk_mul_f32 v[50:51], v[50:51], v[138:139]
	v_pk_mul_f32 v[28:29], v[28:29], v[190:191] op_sel_hi:[1,0]
	v_pk_mul_f32 v[30:31], v[30:31], v[190:191] op_sel_hi:[1,0]
	v_pk_mul_f32 v[28:29], v[28:29], v[140:141]
	v_pk_mul_f32 v[30:31], v[30:31], v[142:143]
	v_pk_mul_f32 v[24:25], v[24:25], v[190:191] op_sel_hi:[1,0]
	v_pk_mul_f32 v[26:27], v[26:27], v[190:191] op_sel_hi:[1,0]
	v_pk_mul_f32 v[24:25], v[24:25], v[244:245]
	v_pk_mul_f32 v[26:27], v[26:27], v[246:247]
	global_store_dwordx4 v154, v[52:55], s[100:101] offset:0 nt
	global_store_dwordx4 v154, v[48:51], s[100:101] offset:64 nt
	global_store_dwordx4 v154, v[28:31], s[100:101] offset:512 nt
	global_store_dwordx4 v154, v[24:27], s[100:101] offset:576 nt
	v_add_u32_e32 v154, 160, v152
	v_lshl_add_u32 v154, v154, 13, v153
	v_pk_mul_f32 v[44:45], v[44:45], v[192:193] op_sel_hi:[1,0]
	v_pk_mul_f32 v[46:47], v[46:47], v[192:193] op_sel_hi:[1,0]
	v_pk_mul_f32 v[44:45], v[44:45], v[132:133]
	v_pk_mul_f32 v[46:47], v[46:47], v[134:135]
	v_pk_mul_f32 v[32:33], v[32:33], v[192:193] op_sel_hi:[1,0]
	v_pk_mul_f32 v[34:35], v[34:35], v[192:193] op_sel_hi:[1,0]
	v_pk_mul_f32 v[32:33], v[32:33], v[136:137]
	v_pk_mul_f32 v[34:35], v[34:35], v[138:139]
	v_pk_mul_f32 v[20:21], v[20:21], v[192:193] op_sel_hi:[1,0]
	v_pk_mul_f32 v[22:23], v[22:23], v[192:193] op_sel_hi:[1,0]
	v_pk_mul_f32 v[20:21], v[20:21], v[140:141]
	v_pk_mul_f32 v[22:23], v[22:23], v[142:143]
	v_pk_mul_f32 v[12:13], v[12:13], v[192:193] op_sel_hi:[1,0]
	v_pk_mul_f32 v[14:15], v[14:15], v[192:193] op_sel_hi:[1,0]
	v_pk_mul_f32 v[12:13], v[12:13], v[244:245]
	v_pk_mul_f32 v[14:15], v[14:15], v[246:247]
	global_store_dwordx4 v154, v[44:47], s[100:101] offset:0 nt
	global_store_dwordx4 v154, v[32:35], s[100:101] offset:64 nt
	global_store_dwordx4 v154, v[20:23], s[100:101] offset:512 nt
	global_store_dwordx4 v154, v[12:15], s[100:101] offset:576 nt
	v_add_u32_e32 v154, 176, v152
	v_lshl_add_u32 v154, v154, 13, v153
	v_pk_mul_f32 v[16:17], v[16:17], v[194:195] op_sel_hi:[1,0]
	v_pk_mul_f32 v[18:19], v[18:19], v[194:195] op_sel_hi:[1,0]
	v_pk_mul_f32 v[16:17], v[16:17], v[132:133]
	v_pk_mul_f32 v[18:19], v[18:19], v[134:135]
	v_pk_mul_f32 v[8:9], v[8:9], v[194:195] op_sel_hi:[1,0]
	v_pk_mul_f32 v[10:11], v[10:11], v[194:195] op_sel_hi:[1,0]
	v_pk_mul_f32 v[8:9], v[8:9], v[136:137]
	v_pk_mul_f32 v[10:11], v[10:11], v[138:139]
	v_pk_mul_f32 v[4:5], v[4:5], v[194:195] op_sel_hi:[1,0]
	v_pk_mul_f32 v[6:7], v[6:7], v[194:195] op_sel_hi:[1,0]
	v_pk_mul_f32 v[4:5], v[4:5], v[140:141]
	v_pk_mul_f32 v[6:7], v[6:7], v[142:143]
	v_pk_mul_f32 v[0:1], v[0:1], v[194:195] op_sel_hi:[1,0]
	v_pk_mul_f32 v[2:3], v[2:3], v[194:195] op_sel_hi:[1,0]
	v_pk_mul_f32 v[0:1], v[0:1], v[244:245]
	v_pk_mul_f32 v[2:3], v[2:3], v[246:247]
	global_store_dwordx4 v154, v[16:19], s[100:101] offset:0 nt
	global_store_dwordx4 v154, v[8:11], s[100:101] offset:64 nt
	global_store_dwordx4 v154, v[4:7], s[100:101] offset:512 nt
	global_store_dwordx4 v154, v[0:3], s[100:101] offset:576 nt
	s_branch .LBB0_1807
